# cvt2+unpk+ P3 start skew 13us for odd (wg>>3) workgroups to de-phase chain-epilogue gate loads within each XCD
# baseline (speedup 1.0000x reference)
.LBB0_483:
	s_lshr_b32 s98, s2, 3
	s_and_b32 s98, s98, 1
	s_mul_i32 s98, s98, 1300
	s_cmp_eq_u32 s98, 0
	s_cbranch_scc1 .Lskew3_done
	s_memrealtime s[100:101]
	s_waitcnt lgkmcnt(0)
	s_mov_b32 s99, s100
.Lskew3_spin:
	s_sleep 8
	s_memrealtime s[100:101]
	s_waitcnt lgkmcnt(0)
	s_sub_u32 s100, s100, s99
	s_cmp_lt_u32 s100, s98
	s_cbranch_scc1 .Lskew3_spin
